# GLA state tiles stored MFMA-fragment-major (coalesced state loads in GLA output phase)
# speedup vs baseline: 1.0195x; 1.0100x over previous
; __device__ __forceinline__ void gla_summ_unit(const P& p, int unit, const SummRaw& raw) {
;     ...
;   int fr = lane & 15, fq = lane >> 4;
; #pragma unroll 1
;   for (int tI = 0; tI < 8; ++tI) {
;     int tile = wid * 8 + tI;
;     int dir = tile >> 5, dkt = (tile >> 3) & 3, dvt = tile & 7;
;     const u16* Asrc = (dir ? kdbT : kdfT) + (dkt * 16 + fr) * LP + fq * 8;
;     const u16* Bsrc = vT + (dvt * 16 + fr) * LP + fq * 8;
;     f32x4 d = {0.f, 0.f, 0.f, 0.f};
; #pragma unroll
;     for (int ks = 0; ks < 2; ++ks) {
;       bf16x8 a = *(const bf16x8*)(Asrc + ks * 32);
;       bf16x8 b = *(const bf16x8*)(Bsrc + ks * 32);
;       d = __builtin_amdgcn_mfma_f32_16x16x32_bf16(a, b, d, 0, 0, 0);
;     }
;     uint2 w; w.x = pack2(d[0], d[1]); w.y = pack2(d[2], d[3]);
;     *(uint2*)(kvout + (size_t)(unit * 2 + dir) * 8192 + (dvt * 16 + fr) * 64 + dkt * 16 + fq * 4) = w;
;   }
.LBB0_226:
	s_or_b64 exec, exec, s[26:27]
	v_and_b32_e32 v31, 15, v51
	v_cmp_gt_u32_e32 vcc, s40, v43
	v_lshlrev_b32_e32 v9, 4, v45
	v_ashrrev_i32_e32 v44, 8, v43
	v_cndmask_b32_e32 v8, v49, v50, vcc
	v_and_or_b32 v9, v9, 48, v31
	s_ashr_i32 s21, s20, 31
	v_add_u32_e32 v8, 16, v8
	v_mul_u32_u24_e32 v9, 0x90, v9
	v_and_b32_e32 v28, 48, v28
	v_mul_u32_u24_e32 v29, 0x90, v31
	v_ashrrev_i32_e32 v45, 31, v44
	v_add3_u32 v12, v8, v9, v28
	v_add3_u32 v30, v29, v28, 16
	v_lshl_add_u64 v[28:29], v[44:45], 0, s[20:21]
	s_waitcnt lgkmcnt(0)
	s_barrier
	ds_read_b128 v[8:11], v12
	ds_read_b128 v[12:15], v12 offset:64
	v_lshlrev_b64 v[28:29], 14, v[28:29]
	v_lshl_or_b32 v28, v31, 4, v28
	v_lshrrev_b32_e32 v31, 1, v43
	v_and_b32_e32 v34, 48, v51
	v_and_b32_e32 v31, 0x60, v31
	v_lshrrev_b32_e32 v34, 1, v34
	v_lshlrev_b32_e32 v31, 4, v31
	v_and_b32_e32 v45, 16, v34
	v_and_b32_e32 v34, 8, v34
	v_lshlrev_b32_e32 v45, 4, v45
	v_or3_b32 v28, v28, v31, v34
	v_or_b32_e32 v28, v28, v45
	v_lshl_add_u64 v[28:29], s[10:11], 0, v[28:29]
	s_mov_b32 s0, 0

; __device__ void phase_gla_scan(const P& p) {
;   u16* kv = (u16*)((char*)p.out + OUT_KV);
;   const float* dec = (const float*)(p.ws + OFF_DEC);
;   int tid = opaque_tid(p);
;   for (int it = blockIdx.x; it < 768; it += gridDim.x) {
;     int chunk0, nc, q;
;     if (it < 256) { q = it; int seq = q >> 6; chunk0 = 512 + seq * 128; nc = 128; q &= 63; }
;     else { q = it - 256; int seq = q >> 6; chunk0 = seq * 64; nc = 64; q &= 63; }
;     int h = q >> 4, dir = (q >> 3) & 1, sl = q & 7;
;     int e0 = sl * 1024 + tid * 2;
;     int dk = e0 & 63;
;     float s0 = 0.f, s1 = 0.f;
;     for (int n8 = 0; n8 < nc; n8 += 8) {
;       unsigned kvv[8]; float2 dd[8];
; #pragma unroll
;       for (int i = 0; i < 8; ++i) {
;         int n = n8 + i;
;         int chunk = dir == 0 ? chunk0 + n : chunk0 + nc - 1 - n;
;         size_t base = (size_t)((chunk * 4 + h) * 2 + dir);
;         kvv[i] = *(const unsigned*)(kv + base * 8192 + e0);
;         dd[i] = *(const float2*)(dec + base * 64 + dk);
.LBB0_321:
	s_or_b64 exec, exec, s[0:1]
	s_cmpk_gt_i32 s2, 0x2ff
	s_waitcnt lgkmcnt(0)
	s_barrier
	v_mbcnt_lo_u32_b32 v0, -1, 0
	v_mbcnt_hi_u32_b32 v0, -1, v0
	s_cbranch_scc1 .LBB0_330
	v_readlane_b32 s0, v255, 0
	s_lshl_b32 s0, s0, 1
	s_and_b32 s0, s0, 0xffffff80
	v_lshl_add_u32 v8, v0, 1, s0
	v_and_b32_e32 v0, 3, v0
	v_lshlrev_b32_e32 v0, 3, v0
	s_lshr_b32 s0, s33, 1
	v_add_u32_e32 v0, s0, v0
	v_mov_b32_e32 v1, 0
	v_lshl_add_u64 v[0:1], s[34:35], 0, v[0:1]
	s_mov_b64 s[0:1], 0x1f400000
	v_lshl_add_u64 v[0:1], v[0:1], 0, s[0:1]
	s_mov_b32 s3, s2

; __device__ __forceinline__ float bf2f(u16 h) { return __uint_as_float(((unsigned)h) << 16); }
; #define LBAR do { asm volatile("s_waitcnt lgkmcnt(0)" ::: "memory"); __builtin_amdgcn_s_barrier(); } while (0)
; __device__ __forceinline__ void gla_cumsum(const P& p, uint4 a, uint4 b, char* sm) {
;     ...
;     int s = tid >> 3, d0 = (tid & 7) * 8;
;     const u16* pa = (const u16*)&a; const u16* pb = (const u16*)&b;
; #pragma unroll
;     for (int e = 0; e < 8; ++e) { bF[s * 65 + d0 + e] = bf2f(pa[e]); bB[s * 65 + d0 + e] = bf2f(pb[e]); }
;   }
;   LBAR;
; __device__ __forceinline__ void gla_out_unit(const P& p, int unit, const OutRaw& raw) {
;   extern __shared__ __attribute__((aligned(16))) u16 shm[];
;   char* sm = (char*)shm;
;   int chunk = unit >> 2, h = unit & 3;
;   int tid = opaque_tid(p), lane = tid & 63, wid = tid >> 6;
;   bf16x8 sB[4][2][2];
;   uint2 rav[4];
;   {
;     int fr = lane & 15, fq = lane >> 4, tt = wid >> 1, dvh = wid & 1;
;     const u16* Sst = (const u16*)((const char*)p.out + OUT_KV) + (size_t)(unit * 2) * 8192;
;     const u16* ra = (const u16*)(p.ws + OFF_RA);
; #pragma unroll
;     for (int i = 0; i < 4; ++i) {
;       int dvt = dvh * 4 + i;
; #pragma unroll
;       for (int ks = 0; ks < 2; ++ks) {
;         sB[i][ks][0] = *(const bf16x8*)(Sst + (dvt * 16 + fr) * 64 + ks * 32 + fq * 8);
;         sB[i][ks][1] = *(const bf16x8*)(Sst + 8192 + (dvt * 16 + fr) * 64 + ks * 32 + fq * 8);
;       }
;       rav[i] = *(const uint2*)(ra + ((size_t)unit * 128 + dvt * 16 + fr) * 64 + tt * 16 + fq * 4);
;     }
;   }
.LBB0_385:
	s_mov_b32 s30, s2
	s_add_i32 s2, s2, s70
	s_cmpk_gt_i32 s2, 0xfff
	s_cselect_b64 s[28:29], -1, 0
	s_cmpk_lt_i32 s2, 0x1000
	s_cselect_b32 s0, s2, s30
	s_lshl_b32 s1, s0, 4
	s_andn2_b32 s1, s1, 63
	s_waitcnt vmcnt(0)
	v_mov_b64_e32 v[32:33], v[16:17]
	v_add_u32_e32 v16, s1, v97
	v_ashrrev_i32_e32 v17, 31, v16
	s_lshl_b32 s1, s0, 6
	v_lshlrev_b64 v[16:17], 8, v[16:17]
	s_and_b32 s1, s1, 0xc0
	v_or_b32_e32 v16, s1, v16
	s_ashr_i32 s1, s0, 31
	s_lshl_b64 s[0:1], s[0:1], 14
	v_or_b32_e32 v16, v16, v96
	s_add_u32 s0, s18, s0
	v_lshlrev_b64 v[16:17], 1, v[16:17]
	s_addc_u32 s1, s19, s1
	v_mov_b64_e32 v[40:41], v[20:21]
	v_mov_b64_e32 v[34:35], v[18:19]
	v_lshl_add_u64 v[18:19], s[12:13], 0, v[16:17]
	v_lshl_add_u64 v[20:21], s[14:15], 0, v[16:17]
	v_lshl_add_u64 v[22:23], s[10:11], 0, v[16:17]
	v_lshl_add_u64 v[16:17], s[20:21], 0, v[16:17]
	v_lshl_add_u64 v[24:25], v[100:101], 1, s[0:1]
	v_lshlrev_b32_e32 v98, 1, v96
	v_lshl_add_u64 v[26:27], v[102:103], 1, s[0:1]
	s_lshl_b32 s0, s30, 1
	v_lshl_add_u64 v[24:25], v[24:25], 0, v[98:99]
	v_lshl_add_u64 v[26:27], v[26:27], 0, v[98:99]
	s_ashr_i32 s1, s0, 31
	v_and_b32_e32 v134, 0xffff0000, v0
	v_lshlrev_b32_e32 v135, 16, v1
	v_and_b32_e32 v142, 0xffff0000, v1
	v_and_b32_e32 v143, 0xffff0000, v2
	v_lshlrev_b32_e32 v144, 16, v3
	v_and_b32_e32 v145, 0xffff0000, v3
	v_and_b32_e32 v146, 0xffff0000, v4
	v_lshlrev_b32_e32 v147, 16, v5
	v_and_b32_e32 v148, 0xffff0000, v5
	v_and_b32_e32 v149, 0xffff0000, v6
	v_lshlrev_b32_e32 v150, 16, v7
	v_and_b32_e32 v151, 0xffff0000, v7
	v_lshlrev_b32_e32 v152, 16, v0
	v_lshlrev_b32_e32 v153, 16, v4
	v_lshlrev_b32_e32 v154, 16, v2
	v_lshlrev_b32_e32 v155, 16, v6
	v_lshlrev_b32_e32 v126, 16, v13
	v_lshlrev_b32_e32 v130, 16, v12
	v_and_b32_e32 v127, 0xffff0000, v13
	v_and_b32_e32 v131, 0xffff0000, v12
	v_lshlrev_b32_e32 v124, 16, v9
	v_lshlrev_b32_e32 v128, 16, v8
	v_and_b32_e32 v125, 0xffff0000, v9
	v_and_b32_e32 v129, 0xffff0000, v8
	v_lshlrev_b32_e32 v116, 16, v15
	v_lshlrev_b32_e32 v122, 16, v14
	v_and_b32_e32 v117, 0xffff0000, v15
	v_and_b32_e32 v123, 0xffff0000, v14
	v_lshlrev_b32_e32 v118, 16, v11
	v_lshlrev_b32_e32 v120, 16, v10
	v_and_b32_e32 v119, 0xffff0000, v11
	v_and_b32_e32 v121, 0xffff0000, v10
	global_load_dwordx4 v[12:15], v[22:23], off
	global_load_dwordx4 v[8:11], v[16:17], off
	global_load_dwordx4 v[0:3], v[18:19], off
	global_load_dwordx4 v[4:7], v[20:21], off
	s_nop 0
	global_load_dwordx4 v[16:19], v[26:27], off
	global_load_dwordx4 v[20:23], v[24:25], off
	v_mbcnt_lo_u32_b32 v137, -1, 0
	v_mbcnt_hi_u32_b32 v137, -1, v137
	s_lshl_b64 s[0:1], s[0:1], 14
	v_add_u32_e32 v141, s33, v137
	v_ashrrev_i32_e32 v136, 7, v141
	s_add_u32 s0, s50, s0
	v_bfe_u32 v156, v137, 4, 2
	v_lshlrev_b32_e32 v114, 4, v136
	s_addc_u32 s1, s51, s1
	s_ashr_i32 s31, s30, 31
	v_ashrrev_i32_e32 v140, 6, v141
	v_and_b32_e32 v139, 15, v137
	v_lshlrev_b32_e32 v112, 8, v156
	v_mov_b32_e32 v113, v99
	v_ashrrev_i32_e32 v115, 31, v114
	s_lshl_b64 s[4:5], s[30:31], 7
	v_and_b32_e32 v138, 1, v140
	v_lshlrev_b32_e32 v98, 3, v156
	v_lshl_add_u64 v[24:25], s[0:1], 0, v[112:113]
	v_lshlrev_b32_e32 v112, 4, v156
	v_lshl_add_u64 v[28:29], v[114:115], 1, s[16:17]
	v_lshlrev_b32_e32 v49, 4, v139
	v_lshl_add_u64 v[26:27], v[24:25], 0, s[22:23]
	v_or_b32_e32 v113, s4, v139
	v_lshl_add_u64 v[104:105], v[28:29], 0, v[98:99]
	v_lshl_or_b32 v28, v138, 13, v49
	v_mov_b32_e32 v29, v99
	v_lshlrev_b32_e32 v115, 6, v138
	v_lshl_add_u64 v[30:31], v[24:25], 0, v[28:29]
	v_lshl_add_u64 v[28:29], v[26:27], 0, v[28:29]
	v_or_b32_e32 v132, v113, v115
	v_mov_b32_e32 v133, s5
	v_lshlrev_b32_e32 v48, 2, v138
	global_load_dwordx4 v[72:75], v[30:31], off
	global_load_dwordx4 v[36:39], v[30:31], off offset:1024
	global_load_dwordx4 v[68:71], v[28:29], off
	global_load_dwordx4 v[44:47], v[28:29], off offset:1024
	v_lshlrev_b64 v[28:29], 7, v[132:133]
	v_lshl_add_u64 v[28:29], v[104:105], 0, v[28:29]
	v_or_b32_e32 v50, 1, v48
	global_load_dwordx2 v[110:111], v[28:29], off
	v_lshl_or_b32 v28, v50, 11, v49
	v_mov_b32_e32 v29, v99
	v_lshl_add_u64 v[30:31], v[24:25], 0, v[28:29]
	v_lshl_add_u64 v[28:29], v[26:27], 0, v[28:29]
	v_lshl_or_b32 v132, v50, 4, v113
	global_load_dwordx4 v[92:95], v[30:31], off
	global_load_dwordx4 v[80:83], v[30:31], off offset:1024
	global_load_dwordx4 v[88:91], v[28:29], off
	global_load_dwordx4 v[84:87], v[28:29], off offset:1024
	v_lshlrev_b64 v[28:29], 7, v[132:133]
	v_lshl_add_u64 v[28:29], v[104:105], 0, v[28:29]
	v_or_b32_e32 v50, 2, v48
	global_load_dwordx2 v[108:109], v[28:29], off
	v_lshl_or_b32 v28, v50, 11, v49
	v_mov_b32_e32 v29, v99
	v_lshl_add_u64 v[30:31], v[24:25], 0, v[28:29]
	v_lshl_add_u64 v[28:29], v[26:27], 0, v[28:29]
	v_lshl_or_b32 v132, v50, 4, v113
	global_load_dwordx4 v[60:63], v[30:31], off
	global_load_dwordx4 v[56:59], v[30:31], off offset:1024
	global_load_dwordx4 v[76:79], v[28:29], off
	global_load_dwordx4 v[64:67], v[28:29], off offset:1024
	v_lshlrev_b64 v[28:29], 7, v[132:133]
	v_lshl_add_u64 v[28:29], v[104:105], 0, v[28:29]
	v_or_b32_e32 v132, 3, v48
	global_load_dwordx2 v[106:107], v[28:29], off
	v_lshl_or_b32 v28, v132, 11, v49
	v_lshl_or_b32 v132, v132, 4, v113
	v_mov_b32_e32 v29, v99
	v_lshlrev_b64 v[132:133], 7, v[132:133]
	v_lshl_add_u64 v[24:25], v[24:25], 0, v[28:29]
	v_lshl_add_u64 v[26:27], v[26:27], 0, v[28:29]
	v_lshl_add_u64 v[104:105], v[104:105], 0, v[132:133]
	global_load_dwordx4 v[52:55], v[24:25], off
	global_load_dwordx4 v[28:31], v[24:25], off offset:1024
	global_load_dwordx4 v[48:51], v[26:27], off
	s_nop 0
	global_load_dwordx4 v[24:27], v[26:27], off offset:1024
	s_mov_b64 s[40:41], -1
	global_load_dwordx2 v[104:105], v[104:105], off
	v_mbcnt_lo_u32_b32 v113, -1, 0
	v_mbcnt_hi_u32_b32 v113, -1, v113
	s_mov_b32 s31, 0
	v_add_u32_e32 v157, s33, v113
	v_lshlrev_b32_e32 v132, 3, v113
	v_ashrrev_i32_e32 v133, 3, v157
	v_and_b32_e32 v132, 56, v132
	v_mad_u64_u32 v[132:133], s[0:1], v133, s3, v[132:133]
	v_lshl_add_u32 v132, v132, 2, 16
	v_add_u32_e32 v133, 0x4104, v132
	ds_write2_b32 v132, v134, v135 offset0:1 offset1:2
	ds_write2_b32 v133, v146, v147 offset1:1
	v_add_u32_e32 v133, 0x410c, v132
	v_lshlrev_b32_e32 v113, 2, v113
	ds_write2_b32 v132, v142, v154 offset0:3 offset1:4
	ds_write2_b32 v133, v148, v155 offset1:1
	v_add_u32_e32 v133, 0x4114, v132
	ds_write2_b32 v132, v143, v144 offset0:5 offset1:6
	ds_write2_b32 v133, v149, v150 offset1:1
	ds_write2_b32 v132, v152, v145 offset1:7
	v_add_u32_e32 v132, 0x4000, v132
	v_and_b32_e32 v147, 0xfc, v113
	ds_write2_b32 v132, v153, v151 offset0:64 offset1:71
	v_ashrrev_i32_e32 v146, 6, v157
	v_add_u32_e32 v132, 16, v147
	v_mad_u64_u32 v[134:135], s[0:1], v146, s25, v[132:133]
	v_lshl_or_b32 v133, v146, 3, 1
	s_waitcnt lgkmcnt(0)
	s_barrier
; #define LBAR do { asm volatile("s_waitcnt lgkmcnt(0)" ::: "memory"); __builtin_amdgcn_s_barrier(); } while (0)
; __device__ __forceinline__ void gla_cumsum(const P& p, uint4 a, uint4 b, char* sm) {
;     ...
;   {
;     float* segF = (float*)(sm + G_SEG);
;     float* segB = segF + 8 * 64;
;     int dk = tid & 63, seg = tid >> 6;
;     float a = 0.f, c = 0.f;
; #pragma unroll
;     for (int i = 0; i < 8; ++i) { a += bF[(seg * 8 + i) * 65 + dk]; bF[(seg * 8 + i) * 65 + dk] = a; }
; #pragma unroll
;     for (int i = 7; i >= 0; --i) { c += bB[(seg * 8 + i) * 65 + dk]; bB[(seg * 8 + i) * 65 + dk] = c; }
;     segF[seg * 64 + dk] = a; segB[seg * 64 + dk] = c;
;     LBAR;
;     float offF = 0.f, offB = 0.f;
; #pragma unroll
;     for (int s2 = 0; s2 < 8; ++s2) {
;       float f = segF[s2 * 64 + dk], g = segB[s2 * 64 + dk];
;       offF += (s2 < seg) ? f : 0.f;
;       offB += (s2 > seg) ? g : 0.f;
;     }
; #pragma unroll
;     for (int i = 0; i < 8; ++i) { bF[(seg * 8 + i) * 65 + dk] += offF; bB[(seg * 8 + i) * 65 + dk] += offB; }
;   }
;   LBAR;
	ds_read_b32 v113, v134
	v_mad_u64_u32 v[132:133], s[0:1], v133, s27, v[132:133]
	ds_read2_b32 v[142:143], v132 offset1:65
	ds_read2_b32 v[144:145], v132 offset0:130 offset1:195
	s_waitcnt lgkmcnt(2)
	v_add_f32_e32 v113, 0, v113
	ds_write_b32 v134, v113
	v_add_u32_e32 v148, 0x400, v132
	s_waitcnt lgkmcnt(2)
	v_add_f32_e32 v113, v113, v142
	v_add_f32_e32 v133, v113, v143
	ds_write2_b32 v132, v113, v133 offset1:65
	s_waitcnt lgkmcnt(2)
	v_add_f32_e32 v113, v133, v144
	v_add_f32_e32 v133, v113, v145
	ds_write2_b32 v132, v113, v133 offset0:130 offset1:195
	ds_read2_b32 v[142:143], v148 offset0:4 offset1:69
	v_add_u32_e32 v149, 0x4400, v132
	v_add_u32_e32 v150, 0x4200, v132
	v_add_u32_e32 v151, 0x4000, v132
	v_cmp_lt_i32_e32 vcc, 0, v146
	s_waitcnt lgkmcnt(0)
	v_add_f32_e32 v113, v133, v142
	v_add_f32_e32 v133, v113, v143
	ds_write2_b32 v148, v113, v133 offset0:4 offset1:69
	ds_read_b32 v113, v132 offset:1560
	ds_read_b32 v135, v132 offset:18200
	v_or_b32_e32 v154, 0x500, v147
	v_add_u32_e32 v155, s84, v154
	v_add_u32_e32 v154, s42, v154
	s_waitcnt lgkmcnt(1)
	v_add_f32_e32 v133, v133, v113
	s_waitcnt lgkmcnt(0)
	v_add_f32_e32 v113, 0, v135
	ds_write_b32 v132, v133 offset:1560
	ds_write_b32 v132, v113 offset:18200
	ds_read2_b32 v[142:143], v149 offset0:68 offset1:133
	s_waitcnt lgkmcnt(0)
	v_add_f32_e32 v113, v113, v143
	v_add_f32_e32 v135, v113, v142
	ds_write2_b32 v149, v135, v113 offset0:68 offset1:133
	ds_read2_b32 v[142:143], v150 offset0:66 offset1:131
	ds_read2_b32 v[144:145], v151 offset0:64 offset1:129
	v_lshlrev_b32_e32 v113, 2, v156
	v_or_b32_e32 v156, 0x600, v147
	s_waitcnt lgkmcnt(1)
	v_add_f32_e32 v135, v135, v143
	ds_read_b32 v143, v134 offset:16640
	v_add_f32_e32 v142, v135, v142
	ds_write2_b32 v150, v142, v135 offset0:66 offset1:131
	s_waitcnt lgkmcnt(2)
	v_add_f32_e32 v135, v142, v145
	v_add_f32_e32 v142, v135, v144
	ds_write2_b32 v151, v142, v135 offset0:64 offset1:129
	s_waitcnt lgkmcnt(2)
	v_add_f32_e32 v135, v142, v143
	v_lshlrev_b32_e32 v142, 2, v157
	v_add_u32_e32 v143, s84, v142
	ds_write_b32 v134, v135 offset:16640
	ds_write_b32 v143, v133
	v_add_u32_e32 v133, s42, v142
	v_or_b32_e32 v142, 0x100, v147
	v_or_b32_e32 v144, 0x200, v147
	ds_write_b32 v133, v135
	v_add_u32_e32 v133, s84, v147
	v_add_u32_e32 v135, s42, v147
	v_add_u32_e32 v143, s84, v142
	v_add_u32_e32 v142, s42, v142
	v_add_u32_e32 v145, s84, v144
	v_add_u32_e32 v144, s42, v144
	s_waitcnt lgkmcnt(0)
	s_barrier
	ds_read_b32 v133, v133
	ds_read_b32 v135, v135
	ds_read_b32 v143, v143
	ds_read_b32 v142, v142
	ds_read_b32 v145, v145
	ds_read_b32 v144, v144
	ds_read_b32 v152, v132 offset:1560
	ds_read_b32 v153, v132 offset:18200
	s_waitcnt lgkmcnt(7)
	v_add_f32_e32 v133, 0, v133
	v_cndmask_b32_e32 v133, 0, v133, vcc
	s_waitcnt lgkmcnt(6)
	v_add_f32_e32 v135, 0, v135
	v_cmp_gt_i32_e32 vcc, 0, v146
	v_add_u32_e32 v157, s84, v156
	v_add_u32_e32 v156, s42, v156
	v_cndmask_b32_e32 v135, 0, v135, vcc
	v_cmp_lt_i32_e32 vcc, 1, v146
	s_waitcnt lgkmcnt(5)
	s_nop 0
	v_cndmask_b32_e32 v143, 0, v143, vcc
	v_cmp_gt_i32_e32 vcc, 1, v146
	v_add_f32_e32 v133, v133, v143
	s_waitcnt lgkmcnt(4)
	v_cndmask_b32_e32 v142, 0, v142, vcc
	v_cmp_lt_i32_e32 vcc, 2, v146
	v_add_f32_e32 v135, v135, v142
	s_waitcnt lgkmcnt(3)
	v_cndmask_b32_e32 v142, 0, v145, vcc
	v_cmp_gt_i32_e32 vcc, 2, v146
	v_add_f32_e32 v133, v133, v142
	s_waitcnt lgkmcnt(2)
	v_cndmask_b32_e32 v142, 0, v144, vcc
	v_add_f32_e32 v135, v135, v142
	v_or_b32_e32 v142, 0x300, v147
	v_or_b32_e32 v144, 0x400, v147
	v_add_u32_e32 v143, s84, v142
	v_add_u32_e32 v142, s42, v142
	v_add_u32_e32 v145, s84, v144
	v_add_u32_e32 v144, s42, v144
	ds_read_b32 v143, v143
	ds_read_b32 v142, v142
	ds_read_b32 v145, v145
	ds_read_b32 v144, v144
	ds_read_b32 v155, v155
	ds_read_b32 v154, v154
	ds_read_b32 v157, v157
	ds_read_b32 v156, v156
	v_cmp_lt_i32_e32 vcc, 3, v146
	s_waitcnt lgkmcnt(7)
	s_nop 0
	v_cndmask_b32_e32 v143, 0, v143, vcc
	v_cmp_gt_i32_e32 vcc, 3, v146
	v_add_f32_e32 v133, v133, v143
	v_or_b32_e32 v143, 0x700, v147
	s_waitcnt lgkmcnt(6)
	v_cndmask_b32_e32 v142, 0, v142, vcc
	v_cmp_lt_i32_e32 vcc, 4, v146
	v_add_f32_e32 v135, v135, v142
	s_waitcnt lgkmcnt(5)
	v_cndmask_b32_e32 v142, 0, v145, vcc
	v_cmp_gt_i32_e32 vcc, 4, v146
	v_add_f32_e32 v133, v133, v142
	s_waitcnt lgkmcnt(4)
	v_cndmask_b32_e32 v142, 0, v144, vcc
	v_cmp_lt_i32_e32 vcc, 5, v146
	v_add_f32_e32 v135, v135, v142
	v_add_u32_e32 v144, s84, v143
	s_waitcnt lgkmcnt(3)
	v_cndmask_b32_e32 v142, 0, v155, vcc
	v_cmp_gt_i32_e32 vcc, 5, v146
	v_add_f32_e32 v133, v133, v142
	ds_read_b32 v144, v144
	s_waitcnt lgkmcnt(3)
	v_cndmask_b32_e32 v142, 0, v154, vcc
	v_cmp_lt_i32_e32 vcc, 6, v146
	v_add_f32_e32 v135, v135, v142
	s_waitcnt lgkmcnt(2)
	v_cndmask_b32_e32 v142, 0, v157, vcc
	v_cmp_gt_i32_e32 vcc, 6, v146
	v_add_f32_e32 v133, v133, v142
	s_waitcnt lgkmcnt(1)
	v_cndmask_b32_e32 v142, 0, v156, vcc
	v_add_f32_e32 v135, v135, v142
	v_add_u32_e32 v142, s42, v143
	ds_read_b32 v145, v142
	v_cmp_lt_i32_e32 vcc, 7, v146
	s_waitcnt lgkmcnt(1)
	s_nop 0
	v_cndmask_b32_e32 v142, 0, v144, vcc
	v_add_f32_e32 v133, v133, v142
	ds_read2st64_b32 v[142:143], v134 offset1:65
	v_cmp_gt_i32_e32 vcc, 7, v146
	s_waitcnt lgkmcnt(1)
	s_nop 0
	v_cndmask_b32_e32 v144, 0, v145, vcc
	v_add_f32_e32 v154, v135, v144
	ds_read2_b32 v[144:145], v132 offset1:65
	ds_read2_b32 v[146:147], v151 offset0:64 offset1:129
	s_waitcnt lgkmcnt(2)
	v_add_f32_e32 v135, v133, v142
	v_add_f32_e32 v142, v154, v143
	ds_write2st64_b32 v134, v135, v142 offset1:65
	ds_read2_b32 v[134:135], v132 offset0:130 offset1:195
	ds_read2_b32 v[142:143], v150 offset0:66 offset1:131
	s_waitcnt lgkmcnt(4)
	v_add_f32_e32 v144, v133, v144
	v_add_f32_e32 v145, v133, v145
	s_waitcnt lgkmcnt(3)
	v_add_f32_e32 v146, v154, v146
	ds_write2_b32 v132, v144, v145 offset1:65
	v_add_f32_e32 v144, v154, v147
	ds_write2_b32 v151, v146, v144 offset0:64 offset1:129
	s_waitcnt lgkmcnt(3)
	v_add_f32_e32 v146, v133, v134
	v_add_f32_e32 v147, v133, v135
	ds_read2_b32 v[134:135], v148 offset0:4 offset1:69
	ds_read2_b32 v[144:145], v149 offset0:68 offset1:133
	s_waitcnt lgkmcnt(4)
	v_add_f32_e32 v142, v154, v142
	ds_write2_b32 v132, v146, v147 offset0:130 offset1:195
	v_add_f32_e32 v143, v154, v143
	s_waitcnt lgkmcnt(2)
	v_add_f32_e32 v134, v133, v134
	v_add_f32_e32 v135, v133, v135
	v_add_f32_e32 v133, v133, v152
	ds_write_b32 v132, v133 offset:1560
	v_add_f32_e32 v133, v154, v153
	ds_write_b32 v132, v133 offset:18200
	v_lshlrev_b32_e32 v132, 3, v137
	ds_write2_b32 v150, v142, v143 offset0:66 offset1:131
	s_waitcnt lgkmcnt(4)
	v_add_f32_e32 v142, v154, v144
	ds_write2_b32 v148, v134, v135 offset0:4 offset1:69
	v_add_f32_e32 v134, v154, v145
	v_ashrrev_i32_e32 v133, 3, v141
	v_and_b32_e32 v132, 56, v132
	ds_write2_b32 v149, v142, v134 offset0:68 offset1:133
	v_mad_u64_u32 v[134:135], s[0:1], v133, s3, v[132:133]
	v_lshl_add_u32 v150, v134, 2, 16
	v_add_u32_e32 v142, 0x4100, v150
	s_waitcnt lgkmcnt(0)
	s_barrier
; __device__ __forceinline__ float bf2f(u16 h) { return __uint_as_float(((unsigned)h) << 16); }
; #define LBAR do { asm volatile("s_waitcnt lgkmcnt(0)" ::: "memory"); __builtin_amdgcn_s_barrier(); } while (0)
; __device__ __forceinline__ void gla_out_unit(const P& p, int unit, const OutRaw& raw) {
;     ...
;   {
;     int s = tid >> 3, d0 = (tid & 7) * 8;
;     const u16* pq = (const u16*)&raw.q; const u16* pk = (const u16*)&raw.k;
;     u16 oqf[8], oqb[8], okf[8], okb[8];
; #pragma unroll
;     for (int e = 0; e < 8; ++e) {
;       float bf = bF[s * 65 + d0 + e], bb = bB[s * 65 + d0 + e];
;       float qq = bf2f(pq[e]), kk = bf2f(pk[e]);
;       oqf[e] = f2bf(qq * __expf(bf)); oqb[e] = f2bf(qq * __expf(bb));
;       okf[e] = f2bf(kk * __expf(-bf)); okb[e] = f2bf(kk * __expf(-bb));
;     }
;     *(uint4*)(qf + s * LP + d0) = *(const uint4*)oqf;
;     *(uint4*)(qb + s * LP + d0) = *(const uint4*)oqb;
;     *(uint4*)(kf + s * LP + d0) = *(const uint4*)okf;
;     *(uint4*)(kb + s * LP + d0) = *(const uint4*)okb;
;     *(uint4*)(vT + (tid >> 3) * LP + (tid & 7) * 8) = raw.v0;
;     *(uint4*)(vT + ((tid + 512) >> 3) * LP + (tid & 7) * 8) = raw.v1;
;   }
;   LBAR;
;   int fr = lane & 15, fq = lane >> 4;
	ds_read2_b32 v[134:135], v150 offset1:1
	ds_read2_b32 v[142:143], v142 offset1:1
	ds_read2_b32 v[144:145], v150 offset0:2 offset1:3
	ds_read2_b32 v[146:147], v150 offset0:4 offset1:5
	ds_read2_b32 v[148:149], v150 offset0:6 offset1:7
	v_add_u32_e32 v151, 0x4108, v150
	s_waitcnt lgkmcnt(3)
	v_mul_f32_e32 v157, 0x3fb8aa3b, v142
	v_mul_f32_e32 v142, 0xbfb8aa3b, v142
	v_exp_f32_e32 v157, v157
	v_exp_f32_e32 v142, v142
	v_add_u32_e32 v152, 0x4110, v150
	v_add_u32_e32 v154, 0x4118, v150
	ds_read2_b32 v[150:151], v151 offset1:1
	ds_read2_b32 v[152:153], v152 offset1:1
	ds_read2_b32 v[154:155], v154 offset1:1
	v_mul_f32_e32 v158, v157, v130
	v_mul_f32_e32 v159, v142, v128
	v_mul_f32_e32 v142, 0x3fb8aa3b, v135
	v_mul_f32_e32 v157, 0x3fb8aa3b, v143
	v_exp_f32_e32 v160, v157
	v_exp_f32_e32 v157, v142
	v_mul_f32_e32 v142, 0xbfb8aa3b, v143
	s_waitcnt lgkmcnt(2)
	v_mul_f32_e32 v143, 0x3fb8aa3b, v150
	v_exp_f32_e32 v143, v143
	v_exp_f32_e32 v142, v142
	v_mul_f32_e32 v156, 0x3fb8aa3b, v134
	v_mul_f32_e32 v134, 0xbfb8aa3b, v134
	v_mul_f32_e32 v162, v143, v126
	v_mul_f32_e32 v143, 0xbfb8aa3b, v144
	v_mul_f32_e32 v135, 0xbfb8aa3b, v135
	v_mul_f32_e32 v161, v142, v129
	v_mul_f32_e32 v142, 0x3fb8aa3b, v144
	v_mul_f32_e32 v150, 0xbfb8aa3b, v150
	v_exp_f32_e32 v144, v143
	v_mul_f32_e32 v143, 0x3fb8aa3b, v145
	v_mul_f32_e32 v163, 0x3fb8aa3b, v151
	v_mul_f32_e32 v145, 0xbfb8aa3b, v145
	v_exp_f32_e32 v156, v156
	v_exp_f32_e32 v134, v134
	v_exp_f32_e32 v135, v135
	v_exp_f32_e32 v142, v142
	v_exp_f32_e32 v150, v150
	v_exp_f32_e32 v143, v143
	v_exp_f32_e32 v163, v163
	v_exp_f32_e32 v145, v145
	v_mul_f32_e32 v160, v160, v131
	v_mul_f32_e32 v150, v150, v124
	v_pk_mul_f32 v[142:143], v[142:143], v[126:127]
	v_pk_mul_f32 v[130:131], v[156:157], v[130:131]
	v_mul_f32_e32 v156, v163, v127
	v_pk_mul_f32 v[126:127], v[144:145], v[124:125]
	v_mul_f32_e32 v124, 0xbfb8aa3b, v151
	v_pk_mul_f32 v[128:129], v[134:135], v[128:129]
	s_waitcnt lgkmcnt(1)
	v_mul_f32_e32 v134, 0x3fb8aa3b, v152
	v_exp_f32_e32 v124, v124
	v_exp_f32_e32 v134, v134
	s_waitcnt lgkmcnt(0)
	v_mul_f32_e32 v145, 0x3fb8aa3b, v154
	v_exp_f32_e32 v145, v145
	v_mul_f32_e32 v151, v124, v125
	v_mul_f32_e32 v157, v134, v122
	v_mul_f32_e32 v125, 0xbfb8aa3b, v146
	v_mul_f32_e32 v134, 0xbfb8aa3b, v152
	v_exp_f32_e32 v135, v134
	v_exp_f32_e32 v134, v125
	v_mul_f32_e32 v125, 0x3fb8aa3b, v153
	v_exp_f32_e32 v144, v125
	v_mul_f32_e32 v124, 0x3fb8aa3b, v146
	v_mul_f32_e32 v125, 0x3fb8aa3b, v147
	v_mul_f32_e32 v164, v145, v116
	v_mul_f32_e32 v163, v144, v123
	v_mul_f32_e32 v144, 0xbfb8aa3b, v153
	v_exp_f32_e32 v144, v144
	v_mul_f32_e32 v145, 0xbfb8aa3b, v154
	v_exp_f32_e32 v124, v124
	v_mul_f32_e32 v152, v135, v120
	v_exp_f32_e32 v125, v125
	v_mul_f32_e32 v135, 0xbfb8aa3b, v147
	v_mul_f32_e32 v153, v144, v121
	v_mul_f32_e32 v144, 0x3fb8aa3b, v148
	v_exp_f32_e32 v147, v145
	v_mul_f32_e32 v145, 0x3fb8aa3b, v149
	v_exp_f32_e32 v144, v144
	v_exp_f32_e32 v145, v145
	v_pk_mul_f32 v[122:123], v[124:125], v[122:123]
	v_mul_f32_e32 v124, 0xbfb8aa3b, v149
	v_mul_f32_e32 v146, 0xbfb8aa3b, v148
	v_mul_f32_e32 v148, v147, v118
	v_pk_mul_f32 v[144:145], v[144:145], v[116:117]
	v_mul_f32_e32 v116, 0x3fb8aa3b, v155
	v_exp_f32_e32 v147, v124
	v_mul_f32_e32 v124, 0xbfb8aa3b, v155
	v_exp_f32_e32 v135, v135
	v_exp_f32_e32 v146, v146
	v_exp_f32_e32 v116, v116
	v_exp_f32_e32 v149, v124
	v_mul_lo_u32 v133, v133, s44
	v_lshlrev_b32_e32 v132, 1, v132
	v_mul_f32_e32 v154, v116, v117
	v_pk_mul_f32 v[124:125], v[146:147], v[118:119]
	v_pk_mul_f32 v[120:121], v[134:135], v[120:121]
	v_mul_f32_e32 v134, v149, v119
	v_add3_u32 v135, 16, v133, v132
	v_cvt_pk_bf16_f32 v119, v144, v145
	v_cvt_pk_bf16_f32 v118, v122, v123
	v_cvt_pk_bf16_f32 v117, v142, v143
	v_cvt_pk_bf16_f32 v116, v130, v131
	ds_write_b128 v135, v[116:119] offset:33280
	v_cvt_pk_bf16_f32 v119, v164, v154
	v_cvt_pk_bf16_f32 v118, v157, v163
	v_cvt_pk_bf16_f32 v117, v162, v156
	v_cvt_pk_bf16_f32 v116, v158, v160
	ds_write_b128 v135, v[116:119] offset:42496
	v_cvt_pk_bf16_f32 v119, v124, v125
	v_cvt_pk_bf16_f32 v118, v120, v121
	v_cvt_pk_bf16_f32 v117, v126, v127
	v_cvt_pk_bf16_f32 v116, v128, v129
	ds_write_b128 v135, v[116:119] offset:51712
	v_cvt_pk_bf16_f32 v119, v148, v134
	v_cvt_pk_bf16_f32 v118, v152, v153
	v_cvt_pk_bf16_f32 v117, v150, v151
	v_cvt_pk_bf16_f32 v116, v159, v161
	ds_write_b128 v135, v[116:119] offset:60928
	v_add3_u32 v116, s45, v133, v132
	ds_write_b128 v116, v[40:43]
	v_add_u32_e32 v40, 0x200, v141
	v_lshrrev_b32_e32 v40, 3, v40
	v_mul_lo_u32 v40, v40, s44
	v_add3_u32 v40, s45, v40, v132
	ds_write_b128 v40, v[32:35]
	s_waitcnt lgkmcnt(0)
	v_or_b32_e32 v32, v114, v139
	v_lshlrev_b32_e32 v40, 5, v140
	v_mul_lo_u32 v33, v32, s46
	v_add_u32_e32 v34, 16, v112
	v_or_b32_e32 v117, v114, v113
	v_lshl_add_u32 v32, v33, 1, v34
	v_mul_lo_u32 v35, v117, s44
	v_or_b32_e32 v116, 1, v117
	v_or_b32_e32 v118, 2, v117
	v_or_b32_e32 v114, 3, v117
	v_and_or_b32 v40, v40, 32, v139
	s_barrier
